# up phase: tail-round units as two 128-row half-units (skip ai=1 MFMAs + stores)
# speedup vs baseline: 1.0221x; 1.0026x over previous
.LBB0_59:
	s_mov_b32 s100, 0
	s_mov_b32 s101, 0
	s_sub_i32 s20, s84, 32
	s_cmp_lt_u32 s20, 10
	s_cselect_b32 s20, 64, 0x48
	s_waitcnt vmcnt(0)
	v_mov_b32_e32 v5, v193
	s_mul_i32 s47, s20, 22
	s_cmp_ge_i32 s96, s47
	v_readfirstlane_b32 s46, v5
	s_cbranch_scc1 .LBB0_71
	v_lshlrev_b32_e32 v3, 4, v5
	v_add_u32_e32 v1, 0x2000, v3
	v_ashrrev_i32_e32 v0, 31, v1
	v_lshrrev_b32_e32 v0, 22, v0
	v_add_u32_e32 v0, v1, v0
	v_ashrrev_i32_e32 v0, 10, v0
	v_mul_i32_i24_e32 v2, 0x400, v0
	v_sub_u32_e32 v1, v1, v2
	v_lshrrev_b32_e32 v2, 4, v1
	v_bitop3_b32 v2, v2, v1, 32 bitop3:0x6c
	v_ashrrev_i32_e32 v1, 31, v2
	v_lshrrev_b32_e32 v1, 26, v1
	v_add_u32_e32 v4, v2, v1
	v_lshlrev_b32_e32 v6, 3, v0
	v_ashrrev_i32_e32 v1, 6, v4
	v_and_b32_e32 v6, -16, v6
	v_readlane_b32 s4, v253, 0
	v_add_u32_e32 v6, v1, v6
	v_and_b32_e32 v7, 3, v1
	s_mov_b32 s4, 0x1fffe0
	v_lshrrev_b32_e32 v8, 2, v6
	v_lshlrev_b32_e32 v9, 1, v6
	v_and_b32_e32 v4, 0xc0, v4
	v_and_or_b32 v7, v6, s4, v7
	v_and_b32_e32 v8, 4, v8
	v_and_b32_e32 v9, 24, v9
	v_sub_u32_e32 v2, v2, v4
	v_or3_b32 v7, v7, v8, v9
	v_lshlrev_b32_e32 v8, 5, v0
	v_ashrrev_i16_sdwa v2, v250, sext(v2) dst_sel:DWORD dst_unused:UNUSED_PAD src0_sel:DWORD src1_sel:BYTE_0
	v_and_b32_e32 v8, 32, v8
	v_bfe_i32 v2, v2, 0, 16
	v_add_lshl_u32 v4, v8, v2, 1
	v_lshl_add_u32 v128, v7, 11, v4
	v_lshl_add_u32 v130, v6, 11, v4
	v_bfe_i32 v4, v5, 27, 1
	v_lshrrev_b32_e32 v4, 22, v4
	v_add_u32_e32 v4, v3, v4
	v_and_b32_e32 v4, 0xfffffc00, v4
	v_sub_u32_e32 v3, v3, v4
	v_lshrrev_b32_e32 v4, 4, v3
	v_bitop3_b32 v6, v4, v3, 32 bitop3:0x6c
	v_ashrrev_i32_e32 v4, 31, v5
	v_lshrrev_b32_e32 v4, 26, v4
	v_ashrrev_i32_e32 v3, 31, v3
	v_add_u32_e32 v4, v5, v4
	v_lshrrev_b32_e32 v3, 26, v3
	v_ashrrev_i32_e32 v4, 6, v4
	s_bitcmp1_b32 s92, 0
	v_add_u32_e32 v3, v6, v3
	v_lshlrev_b32_e32 v7, 3, v4
	s_cselect_b32 s22, 0x2180000, 0
	v_readlane_b32 s12, v253, 8
	s_mov_b64 s[66:67], s[62:63]
	v_ashrrev_i32_e32 v3, 6, v3
	v_and_b32_e32 v7, -16, v7
	v_readlane_b32 s5, v253, 1
	v_readlane_b32 s13, v253, 9
	s_mov_b64 s[64:65], s[60:61]
	s_mov_b64 s[62:63], s[58:59]
	s_mov_b64 s[60:61], s[56:57]
	s_mov_b64 s[58:59], s[54:55]
	s_mov_b64 s[56:57], s[52:53]
	s_mov_b64 s[54:55], s[50:51]
	s_mov_b64 s[52:53], s[48:49]
	s_add_u32 s48, s12, s22
	v_add_u32_e32 v7, v3, v7
	v_and_b32_e32 v8, 3, v3
	s_addc_u32 s49, s13, 0
	s_ashr_i32 s23, s46, 6
	v_and_or_b32 v8, v7, s4, v8
	s_lshr_b32 s51, s47, 3
	v_readlane_b32 s4, v254, 5
	s_ashr_i32 s26, s46, 8
	s_lshl_b32 s50, s23, 10
	s_or_b32 s52, s51, 1
	v_readlane_b32 s5, v254, 6
	s_and_b64 s[28:29], s[4:5], exec
	s_cselect_b32 s22, s52, s51
	v_readlane_b32 s4, v254, 7
	s_mul_i32 s22, s22, s4
	v_readlane_b32 s4, v254, 4
	s_add_i32 s22, s22, s4
	v_lshrrev_b32_e32 v9, 2, v7
	v_lshlrev_b32_e32 v10, 1, v7
	s_mul_hi_i32 s27, s22, 0x2e8ba2e9
	v_and_b32_e32 v9, 4, v9
	v_and_b32_e32 v10, 24, v10
	s_lshr_b32 s28, s27, 31
	s_ashr_i32 s27, s27, 5
	v_or3_b32 v8, v8, v9, v10
	v_mul_i32_i24_e32 v10, 64, v3
	s_add_i32 s27, s27, s28
	v_sub_u32_e32 v6, v6, v10
	s_lshl_b32 s30, s27, 3
	v_lshlrev_b32_e32 v9, 5, v4
	v_ashrrev_i16_sdwa v6, v250, sext(v6) dst_sel:DWORD dst_unused:UNUSED_PAD src0_sel:DWORD src1_sel:BYTE_0
	s_sub_i32 s28, s20, s30
	v_and_b32_e32 v9, 32, v9
	v_bfe_i32 v6, v6, 0, 16
	s_min_i32 s31, s28, 8
	v_add_lshl_u32 v9, v9, v6, 1
	s_sext_i32_i16 s28, s31
	v_lshl_add_u32 v132, v7, 11, v9
	v_cvt_f32_i32_e32 v7, s28
	s_mulk_i32 s27, 0xb0
	s_sub_i32 s27, s22, s27
	v_lshl_add_u32 v184, v8, 11, v9
	v_cvt_f32_i32_e32 v8, s27
	v_rcp_iflag_f32_e32 v9, v7
	s_xor_b32 s22, s27, s28
	s_ashr_i32 s22, s22, 30
	s_or_b32 s22, s22, 1
	v_mul_f32_e32 v9, v8, v9
	v_trunc_f32_e32 v9, v9
	v_fma_f32 v8, -v9, v7, v8
	v_cvt_i32_f32_e32 v9, v9
	v_cmp_ge_f32_e64 s[28:29], |v8|, |v7|
	s_and_b64 s[28:29], s[28:29], exec
	s_cselect_b32 s22, s22, 0
	v_readfirstlane_b32 s28, v9
	s_add_i32 s22, s28, s22
	s_mul_i32 s28, s22, s31
	s_sub_i32 s27, s27, s28
	s_sext_i32_i16 s27, s27
	s_add_i32 s38, s30, s27
	s_ashr_i32 s39, s38, 31
	s_bfe_i64 s[30:31], s[22:23], 0x100000
	s_lshl_b64 s[28:29], s[38:39], 19
	s_lshl_b64 s[30:31], s[30:31], 19
	s_add_u32 s42, s48, s30
	s_addc_u32 s43, s49, s31
	s_add_i32 s39, s50, 0x10000
	s_add_i32 s53, s50, 0x12000
	s_waitcnt vmcnt(0)
	s_mov_b32 m0, s39
	s_add_u32 s40, s54, s28
	global_load_lds_dwordx4 v184, s[42:43]
	s_mov_b32 m0, s53
	s_addc_u32 s41, s55, s29
	s_add_i32 s54, s50, 0x2000
	global_load_lds_dwordx4 v128, s[42:43]
	s_mov_b32 m0, s50
	s_add_u32 s28, s42, 0x40000
	global_load_lds_dwordx4 v132, s[40:41]
	s_mov_b32 m0, s54
	s_addc_u32 s29, s43, 0
	s_add_i32 s55, s50, 0x14000
	global_load_lds_dwordx4 v130, s[40:41]
	s_mov_b32 m0, s55
	s_add_i32 s58, s50, 0x16000
	global_load_lds_dwordx4 v184, s[28:29]
	s_mov_b32 m0, s58
	v_writelane_b32 v255, s84, 43
	global_load_lds_dwordx4 v128, s[28:29]
	s_add_u32 s28, s40, 0x40000
	s_addc_u32 s29, s41, 0
	s_add_i32 s59, s50, 0x4000
	s_mov_b32 m0, s59
	s_add_i32 s60, s50, 0x6000
	global_load_lds_dwordx4 v132, s[28:29]
	s_mov_b32 m0, s60
	v_writelane_b32 v255, s85, 44
	global_load_lds_dwordx4 v130, s[28:29]
	v_writelane_b32 v255, s86, 45
	s_mov_b32 s88, s80
	v_writelane_b32 v255, s87, 46
	s_cmp_lg_u32 s26, 1
	v_readlane_b32 s6, v253, 2
	v_readlane_b32 s7, v253, 3
	v_readlane_b32 s8, v253, 4
	v_readlane_b32 s9, v253, 5
	v_readlane_b32 s10, v253, 6
	v_readlane_b32 s11, v253, 7
	v_readlane_b32 s14, v253, 10
	v_readlane_b32 s15, v253, 11
	v_readlane_b32 s16, v253, 12
	v_readlane_b32 s17, v253, 13
	v_readlane_b32 s18, v253, 14
	v_readlane_b32 s19, v253, 15
	s_cbranch_scc1 .LBB0_62
	s_barrier

.LBB0_63:
	v_readlane_b32 s4, v254, 0
	v_readlane_b32 s5, v254, 1
	s_load_dword s22, s[4:5], 0x0
	s_add_i32 s68, s68, 1
	s_waitcnt lgkmcnt(0)
	s_mul_i32 s26, s68, s22
	s_add_i32 s26, s26, s96
	s_mov_b32 s101, 0
	s_cmp_lt_u32 s92, 3
	s_cselect_b32 s22, 6, 5
	s_movk_i32 s23, 0x100
	s_cselect_b32 s23, 0x60, s23
	s_cmp_lg_u32 s68, s22
	s_cbranch_scc1 .Luph_nohalf
	s_lshl_b32 s22, s22, 8
	s_lshr_b32 s26, s96, 1
	s_add_i32 s26, s26, s22
	s_cmp_lt_u32 s96, s23
	s_cselect_b32 s26, s26, 0x7fffffff
	s_and_b32 s101, s96, 1
	s_add_i32 s101, s101, 1
.Luph_nohalf:
	s_cmp_lt_i32 s26, s47
	s_cselect_b64 s[44:45], -1, 0
	s_cmp_ge_i32 s26, s47
	s_cselect_b64 s[22:23], -1, 0
	s_and_b64 vcc, exec, s[22:23]
	s_cbranch_vccnz .LBB0_65
	s_ashr_i32 s27, s26, 31
	s_lshr_b32 s27, s27, 29
	s_add_i32 s27, s26, s27
	s_ashr_i32 s28, s27, 3
	s_and_b32 s27, s27, -8
	s_sub_i32 s26, s26, s27
	s_cmp_lt_i32 s26, 0
	s_cselect_b32 s27, s52, s51
	s_mul_i32 s26, s27, s26
	s_add_i32 s26, s26, s28
	s_mul_hi_i32 s27, s26, 0x2e8ba2e9
	s_lshr_b32 s28, s27, 31
	s_ashr_i32 s27, s27, 5
	s_add_i32 s27, s27, s28
	s_lshl_b32 s29, s27, 3
	s_sub_i32 s28, s20, s29
	s_min_i32 s30, s28, 8
	s_abs_i32 s28, s30
	v_cvt_f32_u32_e32 v0, s28
	s_sub_i32 s34, 0, s28
	s_mulk_i32 s27, 0xb0
	s_sub_i32 s26, s26, s27
	v_rcp_iflag_f32_e32 v0, v0
	s_abs_i32 s27, s26
	s_xor_b32 s31, s26, s30
	s_ashr_i32 s31, s31, 31
	v_mul_f32_e32 v0, 0x4f7ffffe, v0
	v_cvt_u32_f32_e32 v0, v0
	s_nop 0
	v_readfirstlane_b32 s35, v0
	s_mul_i32 s34, s34, s35
	s_mul_hi_u32 s34, s35, s34
	s_add_i32 s35, s35, s34
	s_mul_hi_u32 s34, s27, s35
	s_mul_i32 s35, s34, s28
	s_sub_i32 s27, s27, s35
	s_add_i32 s36, s34, 1
	s_sub_i32 s35, s27, s28
	s_cmp_ge_u32 s27, s28
	s_cselect_b32 s34, s36, s34
	s_cselect_b32 s27, s35, s27
	s_add_i32 s35, s34, 1
	s_cmp_ge_u32 s27, s28
	s_cselect_b32 s27, s35, s34
	s_xor_b32 s27, s27, s31
	s_sub_i32 s28, s27, s31
	s_mul_i32 s27, s28, s30
	s_sub_i32 s26, s26, s27
	s_add_i32 s30, s26, s29
.LBB0_65:
	s_ashr_i32 s31, s30, 31
	v_readlane_b32 s4, v253, 16
	s_lshl_b64 s[26:27], s[30:31], 19
	v_readlane_b32 s6, v253, 18
	v_readlane_b32 s7, v253, 19
	s_add_u32 s34, s6, s26
	s_addc_u32 s35, s7, s27
	s_cmp_eq_u32 s101, 2
	s_cselect_b32 s26, 0x40000, 0
	s_add_u32 s34, s34, s26
	s_addc_u32 s35, s35, 0
	s_and_b64 s[26:27], s[44:45], exec
	s_cselect_b32 s31, s35, s41
	s_cselect_b32 s80, s34, s40
	s_ashr_i32 s29, s28, 31
	s_lshl_b64 s[26:27], s[28:29], 19
	s_add_u32 s36, s48, s26
	s_addc_u32 s37, s49, s27
	s_and_b64 s[26:27], s[44:45], exec
	s_cselect_b32 s29, s37, s43
	s_cselect_b32 vcc_lo, s36, s42
	s_add_u32 s40, s40, 0x40080
	s_addc_u32 s41, s41, 0
	s_add_u32 s26, s42, 0x100
	v_mov_b32_e32 v0, 0
	s_addc_u32 s27, s43, 0
	s_mov_b32 s96, -2
	v_mov_b32_e32 v1, v0
	v_mov_b32_e32 v2, v0
	v_mov_b32_e32 v3, v0
	v_mov_b32_e32 v8, v0
	v_mov_b32_e32 v9, v0
	v_mov_b32_e32 v10, v0
	v_mov_b32_e32 v11, v0
	v_mov_b32_e32 v16, v0
	v_mov_b32_e32 v17, v0
	v_mov_b32_e32 v18, v0
	v_mov_b32_e32 v19, v0
	v_mov_b32_e32 v24, v0
	v_mov_b32_e32 v25, v0
	v_mov_b32_e32 v26, v0
	v_mov_b32_e32 v27, v0
	v_mov_b32_e32 v32, v0
	v_mov_b32_e32 v33, v0
	v_mov_b32_e32 v34, v0
	v_mov_b32_e32 v35, v0
	v_mov_b32_e32 v40, v0
	v_mov_b32_e32 v41, v0
	v_mov_b32_e32 v42, v0
	v_mov_b32_e32 v43, v0
	v_mov_b32_e32 v48, v0
	v_mov_b32_e32 v49, v0
	v_mov_b32_e32 v50, v0
	v_mov_b32_e32 v51, v0
	v_mov_b32_e32 v56, v0
	v_mov_b32_e32 v57, v0
	v_mov_b32_e32 v58, v0
	v_mov_b32_e32 v59, v0
	v_mov_b32_e32 v4, v0
	v_mov_b32_e32 v5, v0
	v_mov_b32_e32 v6, v0
	v_mov_b32_e32 v7, v0
	v_mov_b32_e32 v12, v0
	v_mov_b32_e32 v13, v0
	v_mov_b32_e32 v14, v0
	v_mov_b32_e32 v15, v0
	v_mov_b32_e32 v20, v0
	v_mov_b32_e32 v21, v0
	v_mov_b32_e32 v22, v0
	v_mov_b32_e32 v23, v0
	v_mov_b32_e32 v28, v0
	v_mov_b32_e32 v29, v0
	v_mov_b32_e32 v30, v0
	v_mov_b32_e32 v31, v0
	v_mov_b32_e32 v36, v0
	v_mov_b32_e32 v37, v0
	v_mov_b32_e32 v38, v0
	v_mov_b32_e32 v39, v0
	v_mov_b32_e32 v44, v0
	v_mov_b32_e32 v45, v0
	v_mov_b32_e32 v46, v0
	v_mov_b32_e32 v47, v0
	v_mov_b32_e32 v52, v0
	v_mov_b32_e32 v53, v0
	v_mov_b32_e32 v54, v0
	v_mov_b32_e32 v55, v0
	v_mov_b32_e32 v60, v0
	v_mov_b32_e32 v61, v0
	v_mov_b32_e32 v62, v0
	v_mov_b32_e32 v63, v0
	v_mov_b32_e32 v64, v0
	v_mov_b32_e32 v65, v0
	v_mov_b32_e32 v66, v0
	v_mov_b32_e32 v67, v0
	v_mov_b32_e32 v72, v0
	v_mov_b32_e32 v73, v0
	v_mov_b32_e32 v74, v0
	v_mov_b32_e32 v75, v0
	v_mov_b32_e32 v80, v0
	v_mov_b32_e32 v81, v0
	v_mov_b32_e32 v82, v0
	v_mov_b32_e32 v83, v0
	v_mov_b32_e32 v88, v0
	v_mov_b32_e32 v89, v0
	v_mov_b32_e32 v90, v0
	v_mov_b32_e32 v91, v0
	v_mov_b32_e32 v96, v0
	v_mov_b32_e32 v97, v0
	v_mov_b32_e32 v98, v0
	v_mov_b32_e32 v99, v0
	v_mov_b32_e32 v104, v0
	v_mov_b32_e32 v105, v0
	v_mov_b32_e32 v106, v0
	v_mov_b32_e32 v107, v0
	v_mov_b32_e32 v112, v0
	v_mov_b32_e32 v113, v0
	v_mov_b32_e32 v114, v0
	v_mov_b32_e32 v115, v0
	v_mov_b32_e32 v120, v0
	v_mov_b32_e32 v121, v0
	v_mov_b32_e32 v122, v0
	v_mov_b32_e32 v123, v0
	v_mov_b32_e32 v68, v0
	v_mov_b32_e32 v69, v0
	v_mov_b32_e32 v70, v0
	v_mov_b32_e32 v71, v0
	v_mov_b32_e32 v76, v0
	v_mov_b32_e32 v77, v0
	v_mov_b32_e32 v78, v0
	v_mov_b32_e32 v79, v0
	v_mov_b32_e32 v84, v0
	v_mov_b32_e32 v85, v0
	v_mov_b32_e32 v86, v0
	v_mov_b32_e32 v87, v0
	v_mov_b32_e32 v92, v0
	v_mov_b32_e32 v93, v0
	v_mov_b32_e32 v94, v0
	v_mov_b32_e32 v95, v0
	v_mov_b32_e32 v100, v0
	v_mov_b32_e32 v101, v0
	v_mov_b32_e32 v102, v0
	v_mov_b32_e32 v103, v0
	v_mov_b32_e32 v108, v0
	v_mov_b32_e32 v109, v0
	v_mov_b32_e32 v110, v0
	v_mov_b32_e32 v111, v0
	v_mov_b32_e32 v116, v0
	v_mov_b32_e32 v117, v0
	v_mov_b32_e32 v118, v0
	v_mov_b32_e32 v119, v0
	v_mov_b32_e32 v124, v0
	v_mov_b32_e32 v125, v0
	v_mov_b32_e32 v126, v0
	v_mov_b32_e32 v127, v0
	v_readlane_b32 s5, v253, 17
	v_readlane_b32 s8, v253, 20
	v_readlane_b32 s9, v253, 21
	v_readlane_b32 s10, v253, 22
	v_readlane_b32 s11, v253, 23
	v_readlane_b32 s12, v253, 24
	v_readlane_b32 s13, v253, 25
	v_readlane_b32 s14, v253, 26
	v_readlane_b32 s15, v253, 27
	v_readlane_b32 s16, v253, 28
	v_readlane_b32 s17, v253, 29
	v_readlane_b32 s18, v253, 30
	v_readlane_b32 s19, v253, 31
.LBB0_66:
	v_or_b32_e32 v142, 0x10000, v140
	v_add_u32_e32 v146, 0x10400, v140
	v_add_u32_e32 v150, 0x10800, v140
	v_add_u32_e32 v154, 0x10c00, v140
	ds_read_b128 v[142:145], v142
	ds_read_b128 v[146:149], v146
	ds_read_b128 v[150:153], v150
	ds_read_b128 v[154:157], v154
	s_add_u32 s42, s40, 0xfffc0080
	s_addc_u32 s43, s41, -1
	s_cmp_eq_u32 s96, 12
	s_cselect_b32 s45, s31, s43
	s_cselect_b32 s44, s80, s42
	s_cselect_b32 s43, s29, s27
	s_cselect_b32 s42, vcc_lo, s26
	s_mov_b32 m0, s69
	v_lshl_add_u64 v[182:183], s[40:41], 0, v[134:135]
	ds_read_b128 v[158:161], v139
	ds_read_b128 v[162:165], v139 offset:1024
	ds_read_b128 v[166:169], v139 offset:2048
	ds_read_b128 v[170:173], v139 offset:3072
	ds_read_b128 v[174:177], v139 offset:4096
	ds_read_b128 v[178:181], v139 offset:5120
	ds_read_b128 v[186:189], v139 offset:6144
	ds_read_b128 v[194:197], v139 offset:7168
	global_load_lds_dwordx4 v[182:183], off
	v_lshl_add_u64 v[182:183], s[40:41], 0, v[136:137]
	s_mov_b32 m0, s70
	s_nop 0
	global_load_lds_dwordx4 v[182:183], off
	s_waitcnt lgkmcnt(8)
	s_barrier
	s_waitcnt lgkmcnt(0)
	s_setprio 1
	s_waitcnt lgkmcnt(0)
	v_mfma_f32_16x16x32_bf16 v[124:127], v[142:145], v[158:161], v[124:127]
	v_mfma_f32_16x16x32_bf16 v[116:119], v[150:153], v[158:161], v[116:119]
	v_mfma_f32_16x16x32_bf16 v[108:111], v[142:145], v[166:169], v[108:111]
	v_mfma_f32_16x16x32_bf16 v[100:103], v[150:153], v[166:169], v[100:103]
	v_mfma_f32_16x16x32_bf16 v[92:95], v[142:145], v[174:177], v[92:95]
	v_mfma_f32_16x16x32_bf16 v[84:87], v[150:153], v[174:177], v[84:87]
	v_mfma_f32_16x16x32_bf16 v[76:79], v[142:145], v[186:189], v[76:79]
	v_mfma_f32_16x16x32_bf16 v[68:71], v[150:153], v[186:189], v[68:71]
	v_mfma_f32_16x16x32_bf16 v[124:127], v[146:149], v[162:165], v[124:127]
	v_mfma_f32_16x16x32_bf16 v[116:119], v[154:157], v[162:165], v[116:119]
	v_mfma_f32_16x16x32_bf16 v[108:111], v[146:149], v[170:173], v[108:111]
	v_mfma_f32_16x16x32_bf16 v[100:103], v[154:157], v[170:173], v[100:103]
	v_mfma_f32_16x16x32_bf16 v[92:95], v[146:149], v[178:181], v[92:95]
	v_mfma_f32_16x16x32_bf16 v[84:87], v[154:157], v[178:181], v[84:87]
	v_mfma_f32_16x16x32_bf16 v[76:79], v[146:149], v[194:197], v[76:79]
	v_mfma_f32_16x16x32_bf16 v[68:71], v[154:157], v[194:197], v[68:71]
	s_setprio 0
	s_barrier
	v_or_b32_e32 v182, 0x14000, v140
	v_add_u32_e32 v183, 0x14400, v140
	ds_read_b128 v[198:201], v182
	ds_read_b128 v[202:205], v183
	v_add_u32_e32 v182, 0x14800, v140
	v_add_u32_e32 v183, 0x14c00, v140
	s_mov_b32 m0, s39
	ds_read_b128 v[206:209], v182
	ds_read_b128 v[210:213], v183
	v_lshl_add_u64 v[182:183], s[42:43], 0, v[184:185]
	global_load_lds_dwordx4 v[182:183], off
	v_lshl_add_u64 v[190:191], s[42:43], 0, v[128:129]
	s_mov_b32 m0, s53
	s_nop 0
	global_load_lds_dwordx4 v[190:191], off
	s_barrier
	s_waitcnt lgkmcnt(0)
	s_setprio 1
	s_waitcnt lgkmcnt(0)
	v_mfma_f32_16x16x32_bf16 v[120:123], v[198:201], v[158:161], v[120:123]
	v_mfma_f32_16x16x32_bf16 v[112:115], v[206:209], v[158:161], v[112:115]
	v_mfma_f32_16x16x32_bf16 v[104:107], v[198:201], v[166:169], v[104:107]
	v_mfma_f32_16x16x32_bf16 v[96:99], v[206:209], v[166:169], v[96:99]
	v_mfma_f32_16x16x32_bf16 v[88:91], v[198:201], v[174:177], v[88:91]
	v_mfma_f32_16x16x32_bf16 v[80:83], v[206:209], v[174:177], v[80:83]
	v_mfma_f32_16x16x32_bf16 v[72:75], v[198:201], v[186:189], v[72:75]
	v_mfma_f32_16x16x32_bf16 v[64:67], v[206:209], v[186:189], v[64:67]
	v_mfma_f32_16x16x32_bf16 v[120:123], v[202:205], v[162:165], v[120:123]
	v_mfma_f32_16x16x32_bf16 v[112:115], v[210:213], v[162:165], v[112:115]
	v_mfma_f32_16x16x32_bf16 v[104:107], v[202:205], v[170:173], v[104:107]
	v_mfma_f32_16x16x32_bf16 v[96:99], v[210:213], v[170:173], v[96:99]
	v_mfma_f32_16x16x32_bf16 v[88:91], v[202:205], v[178:181], v[88:91]
	v_mfma_f32_16x16x32_bf16 v[80:83], v[210:213], v[178:181], v[80:83]
	v_mfma_f32_16x16x32_bf16 v[72:75], v[202:205], v[194:197], v[72:75]
	v_mfma_f32_16x16x32_bf16 v[64:67], v[210:213], v[194:197], v[64:67]
	s_setprio 0
	s_mov_b32 m0, s50
	v_lshl_add_u64 v[214:215], s[44:45], 0, v[132:133]
	s_barrier
	ds_read_b128 v[158:161], v139 offset:16384
	ds_read_b128 v[162:165], v139 offset:17408
	ds_read_b128 v[166:169], v139 offset:18432
	ds_read_b128 v[170:173], v139 offset:19456
	ds_read_b128 v[174:177], v139 offset:20480
	ds_read_b128 v[178:181], v139 offset:21504
	ds_read_b128 v[186:189], v139 offset:22528
	ds_read_b128 v[194:197], v139 offset:23552
	global_load_lds_dwordx4 v[214:215], off
	v_lshl_add_u64 v[216:217], s[44:45], 0, v[130:131]
	s_mov_b32 m0, s54
	s_nop 0
	global_load_lds_dwordx4 v[216:217], off
	s_barrier
	s_waitcnt lgkmcnt(0)
	s_setprio 1
	s_waitcnt lgkmcnt(0)
	s_cmp_lg_u32 s100, 0
	s_cbranch_scc1 .Luph_s2
	v_mfma_f32_16x16x32_bf16 v[60:63], v[142:145], v[158:161], v[60:63]
	v_mfma_f32_16x16x32_bf16 v[52:55], v[150:153], v[158:161], v[52:55]
	v_mfma_f32_16x16x32_bf16 v[44:47], v[142:145], v[166:169], v[44:47]
	v_mfma_f32_16x16x32_bf16 v[36:39], v[150:153], v[166:169], v[36:39]
	v_mfma_f32_16x16x32_bf16 v[28:31], v[142:145], v[174:177], v[28:31]
	v_mfma_f32_16x16x32_bf16 v[20:23], v[150:153], v[174:177], v[20:23]
	v_mfma_f32_16x16x32_bf16 v[12:15], v[142:145], v[186:189], v[12:15]
	v_mfma_f32_16x16x32_bf16 v[4:7], v[150:153], v[186:189], v[4:7]
	v_mfma_f32_16x16x32_bf16 v[60:63], v[146:149], v[162:165], v[60:63]
	v_mfma_f32_16x16x32_bf16 v[52:55], v[154:157], v[162:165], v[52:55]
	v_mfma_f32_16x16x32_bf16 v[44:47], v[146:149], v[170:173], v[44:47]
	v_mfma_f32_16x16x32_bf16 v[36:39], v[154:157], v[170:173], v[36:39]
	v_mfma_f32_16x16x32_bf16 v[28:31], v[146:149], v[178:181], v[28:31]
	v_mfma_f32_16x16x32_bf16 v[20:23], v[154:157], v[178:181], v[20:23]
	v_mfma_f32_16x16x32_bf16 v[12:15], v[146:149], v[194:197], v[12:15]
	v_mfma_f32_16x16x32_bf16 v[4:7], v[154:157], v[194:197], v[4:7]
.Luph_s2:
	s_setprio 0
	s_barrier
	s_add_u32 s66, s42, 0x40000
	s_addc_u32 s67, s43, 0
	s_mov_b32 m0, s55
	v_lshl_add_u64 v[142:143], s[66:67], 0, v[184:185]
	global_load_lds_dwordx4 v[142:143], off
	v_lshl_add_u64 v[142:143], s[66:67], 0, v[128:129]
	s_mov_b32 m0, s58
	s_nop 0
	global_load_lds_dwordx4 v[142:143], off
	s_waitcnt vmcnt(6)
	s_barrier
	s_setprio 1
	s_cmp_lg_u32 s100, 0
	s_cbranch_scc1 .Luph_s3
	v_mfma_f32_16x16x32_bf16 v[56:59], v[198:201], v[158:161], v[56:59]
	v_mfma_f32_16x16x32_bf16 v[48:51], v[206:209], v[158:161], v[48:51]
	v_mfma_f32_16x16x32_bf16 v[40:43], v[198:201], v[166:169], v[40:43]
	v_mfma_f32_16x16x32_bf16 v[32:35], v[206:209], v[166:169], v[32:35]
	v_mfma_f32_16x16x32_bf16 v[24:27], v[198:201], v[174:177], v[24:27]
	v_mfma_f32_16x16x32_bf16 v[16:19], v[206:209], v[174:177], v[16:19]
	v_mfma_f32_16x16x32_bf16 v[8:11], v[198:201], v[186:189], v[8:11]
	v_mfma_f32_16x16x32_bf16 v[0:3], v[206:209], v[186:189], v[0:3]
	v_mfma_f32_16x16x32_bf16 v[56:59], v[202:205], v[162:165], v[56:59]
	v_mfma_f32_16x16x32_bf16 v[48:51], v[210:213], v[162:165], v[48:51]
	v_mfma_f32_16x16x32_bf16 v[40:43], v[202:205], v[170:173], v[40:43]
	v_mfma_f32_16x16x32_bf16 v[32:35], v[210:213], v[170:173], v[32:35]
	v_mfma_f32_16x16x32_bf16 v[24:27], v[202:205], v[178:181], v[24:27]
	v_mfma_f32_16x16x32_bf16 v[16:19], v[210:213], v[178:181], v[16:19]
	v_mfma_f32_16x16x32_bf16 v[8:11], v[202:205], v[194:197], v[8:11]
	v_mfma_f32_16x16x32_bf16 v[0:3], v[210:213], v[194:197], v[0:3]
.Luph_s3:
	s_setprio 0
	v_or_b32_e32 v142, 0x18000, v140
	v_add_u32_e32 v146, 0x18400, v140
	v_add_u32_e32 v150, 0x18800, v140
	v_add_u32_e32 v154, 0x18c00, v140
	s_barrier
	ds_read_b128 v[142:145], v142
	ds_read_b128 v[146:149], v146
	ds_read_b128 v[150:153], v150
	ds_read_b128 v[154:157], v154
	s_add_u32 s44, s44, 0x40000
	s_addc_u32 s45, s45, 0
	s_mov_b32 m0, s59
	v_lshl_add_u64 v[198:199], s[44:45], 0, v[132:133]
	ds_read_b128 v[158:161], v139 offset:32768
	ds_read_b128 v[162:165], v139 offset:33792
	ds_read_b128 v[166:169], v139 offset:34816
	ds_read_b128 v[170:173], v139 offset:35840
	ds_read_b128 v[174:177], v139 offset:36864
	ds_read_b128 v[178:181], v139 offset:37888
	ds_read_b128 v[186:189], v139 offset:38912
	ds_read_b128 v[194:197], v139 offset:39936
	global_load_lds_dwordx4 v[198:199], off
	v_lshl_add_u64 v[198:199], s[44:45], 0, v[130:131]
	s_mov_b32 m0, s60
	s_nop 0
	global_load_lds_dwordx4 v[198:199], off
	s_waitcnt lgkmcnt(8)
	s_barrier
	s_waitcnt lgkmcnt(0)
	s_setprio 1
	s_waitcnt lgkmcnt(0)
	v_mfma_f32_16x16x32_bf16 v[124:127], v[142:145], v[158:161], v[124:127]
	v_mfma_f32_16x16x32_bf16 v[116:119], v[150:153], v[158:161], v[116:119]
	v_mfma_f32_16x16x32_bf16 v[108:111], v[142:145], v[166:169], v[108:111]
	v_mfma_f32_16x16x32_bf16 v[100:103], v[150:153], v[166:169], v[100:103]
	v_mfma_f32_16x16x32_bf16 v[92:95], v[142:145], v[174:177], v[92:95]
	v_mfma_f32_16x16x32_bf16 v[84:87], v[150:153], v[174:177], v[84:87]
	v_mfma_f32_16x16x32_bf16 v[76:79], v[142:145], v[186:189], v[76:79]
	v_mfma_f32_16x16x32_bf16 v[68:71], v[150:153], v[186:189], v[68:71]
	v_mfma_f32_16x16x32_bf16 v[124:127], v[146:149], v[162:165], v[124:127]
	v_mfma_f32_16x16x32_bf16 v[116:119], v[154:157], v[162:165], v[116:119]
	v_mfma_f32_16x16x32_bf16 v[108:111], v[146:149], v[170:173], v[108:111]
	v_mfma_f32_16x16x32_bf16 v[100:103], v[154:157], v[170:173], v[100:103]
	v_mfma_f32_16x16x32_bf16 v[92:95], v[146:149], v[178:181], v[92:95]
	v_mfma_f32_16x16x32_bf16 v[84:87], v[154:157], v[178:181], v[84:87]
	v_mfma_f32_16x16x32_bf16 v[76:79], v[146:149], v[194:197], v[76:79]
	v_mfma_f32_16x16x32_bf16 v[68:71], v[154:157], v[194:197], v[68:71]
	s_setprio 0
	s_barrier
	v_or_b32_e32 v192, 0x1c000, v140
	v_add_u32_e32 v202, 0x1c400, v140
	s_mov_b32 m0, s33
	ds_read_b128 v[198:201], v192
	ds_read_b128 v[202:205], v202
	v_add_u32_e32 v192, 0x1c800, v140
	v_add_u32_e32 v210, 0x1cc00, v140
	v_lshl_add_u64 v[182:183], v[182:183], 0, s[24:25]
	ds_read_b128 v[206:209], v192
	ds_read_b128 v[210:213], v210
	global_load_lds_dwordx4 v[182:183], off
	v_lshl_add_u64 v[182:183], v[190:191], 0, s[24:25]
	s_mov_b32 m0, s61
	s_nop 0
	global_load_lds_dwordx4 v[182:183], off
	s_barrier
	s_waitcnt lgkmcnt(0)
	s_setprio 1
	s_waitcnt lgkmcnt(0)
	v_mfma_f32_16x16x32_bf16 v[120:123], v[198:201], v[158:161], v[120:123]
	v_mfma_f32_16x16x32_bf16 v[112:115], v[206:209], v[158:161], v[112:115]
	v_mfma_f32_16x16x32_bf16 v[104:107], v[198:201], v[166:169], v[104:107]
	v_mfma_f32_16x16x32_bf16 v[96:99], v[206:209], v[166:169], v[96:99]
	v_mfma_f32_16x16x32_bf16 v[88:91], v[198:201], v[174:177], v[88:91]
	v_mfma_f32_16x16x32_bf16 v[80:83], v[206:209], v[174:177], v[80:83]
	v_mfma_f32_16x16x32_bf16 v[72:75], v[198:201], v[186:189], v[72:75]
	v_mfma_f32_16x16x32_bf16 v[64:67], v[206:209], v[186:189], v[64:67]
	v_mfma_f32_16x16x32_bf16 v[120:123], v[202:205], v[162:165], v[120:123]
	v_mfma_f32_16x16x32_bf16 v[112:115], v[210:213], v[162:165], v[112:115]
	v_mfma_f32_16x16x32_bf16 v[104:107], v[202:205], v[170:173], v[104:107]
	v_mfma_f32_16x16x32_bf16 v[96:99], v[210:213], v[170:173], v[96:99]
	v_mfma_f32_16x16x32_bf16 v[88:91], v[202:205], v[178:181], v[88:91]
	v_mfma_f32_16x16x32_bf16 v[80:83], v[210:213], v[178:181], v[80:83]
	v_mfma_f32_16x16x32_bf16 v[72:75], v[202:205], v[194:197], v[72:75]
	v_mfma_f32_16x16x32_bf16 v[64:67], v[210:213], v[194:197], v[64:67]
	s_setprio 0
	s_mov_b32 m0, s62
	v_lshl_add_u64 v[182:183], v[214:215], 0, s[24:25]
	s_barrier
	ds_read_b128 v[158:161], v139 offset:49152
	ds_read_b128 v[162:165], v139 offset:50176
	ds_read_b128 v[166:169], v139 offset:51200
	ds_read_b128 v[170:173], v139 offset:52224
	ds_read_b128 v[174:177], v139 offset:53248
	ds_read_b128 v[178:181], v139 offset:54272
	ds_read_b128 v[186:189], v139 offset:55296
	ds_read_b128 v[194:197], v139 offset:56320
	global_load_lds_dwordx4 v[182:183], off
	v_lshl_add_u64 v[182:183], v[216:217], 0, s[24:25]
	s_mov_b32 m0, s63
	s_nop 0
	global_load_lds_dwordx4 v[182:183], off
	s_barrier
	s_waitcnt lgkmcnt(0)
	s_setprio 1
	s_waitcnt lgkmcnt(0)
	s_cmp_lg_u32 s100, 0
	s_cbranch_scc1 .Luph_s6
	v_mfma_f32_16x16x32_bf16 v[60:63], v[142:145], v[158:161], v[60:63]
	v_mfma_f32_16x16x32_bf16 v[52:55], v[150:153], v[158:161], v[52:55]
	v_mfma_f32_16x16x32_bf16 v[44:47], v[142:145], v[166:169], v[44:47]
	v_mfma_f32_16x16x32_bf16 v[36:39], v[150:153], v[166:169], v[36:39]
	v_mfma_f32_16x16x32_bf16 v[28:31], v[142:145], v[174:177], v[28:31]
	v_mfma_f32_16x16x32_bf16 v[20:23], v[150:153], v[174:177], v[20:23]
	v_mfma_f32_16x16x32_bf16 v[12:15], v[142:145], v[186:189], v[12:15]
	v_mfma_f32_16x16x32_bf16 v[4:7], v[150:153], v[186:189], v[4:7]
	v_mfma_f32_16x16x32_bf16 v[60:63], v[146:149], v[162:165], v[60:63]
	v_mfma_f32_16x16x32_bf16 v[52:55], v[154:157], v[162:165], v[52:55]
	v_mfma_f32_16x16x32_bf16 v[44:47], v[146:149], v[170:173], v[44:47]
	v_mfma_f32_16x16x32_bf16 v[36:39], v[154:157], v[170:173], v[36:39]
	v_mfma_f32_16x16x32_bf16 v[28:31], v[146:149], v[178:181], v[28:31]
	v_mfma_f32_16x16x32_bf16 v[20:23], v[154:157], v[178:181], v[20:23]
	v_mfma_f32_16x16x32_bf16 v[12:15], v[146:149], v[194:197], v[12:15]
	v_mfma_f32_16x16x32_bf16 v[4:7], v[154:157], v[194:197], v[4:7]
.Luph_s6:
	s_setprio 0
	s_barrier
	s_add_u32 s42, s42, 0x40080
	s_addc_u32 s43, s43, 0
	s_mov_b32 m0, s64
	v_lshl_add_u64 v[142:143], s[42:43], 0, v[184:185]
	global_load_lds_dwordx4 v[142:143], off
	v_lshl_add_u64 v[142:143], s[42:43], 0, v[128:129]
	s_mov_b32 m0, s65
	s_nop 0
	global_load_lds_dwordx4 v[142:143], off
	s_waitcnt vmcnt(6)
	s_barrier
	s_setprio 1
	s_cmp_lg_u32 s100, 0
	s_cbranch_scc1 .Luph_s7
	v_mfma_f32_16x16x32_bf16 v[56:59], v[198:201], v[158:161], v[56:59]
	v_mfma_f32_16x16x32_bf16 v[48:51], v[206:209], v[158:161], v[48:51]
	v_mfma_f32_16x16x32_bf16 v[40:43], v[198:201], v[166:169], v[40:43]
	v_mfma_f32_16x16x32_bf16 v[32:35], v[206:209], v[166:169], v[32:35]
	v_mfma_f32_16x16x32_bf16 v[24:27], v[198:201], v[174:177], v[24:27]
	v_mfma_f32_16x16x32_bf16 v[16:19], v[206:209], v[174:177], v[16:19]
	v_mfma_f32_16x16x32_bf16 v[8:11], v[198:201], v[186:189], v[8:11]
	v_mfma_f32_16x16x32_bf16 v[0:3], v[206:209], v[186:189], v[0:3]
	v_mfma_f32_16x16x32_bf16 v[56:59], v[202:205], v[162:165], v[56:59]
	v_mfma_f32_16x16x32_bf16 v[48:51], v[210:213], v[162:165], v[48:51]
	v_mfma_f32_16x16x32_bf16 v[40:43], v[202:205], v[170:173], v[40:43]
	v_mfma_f32_16x16x32_bf16 v[32:35], v[210:213], v[170:173], v[32:35]
	v_mfma_f32_16x16x32_bf16 v[24:27], v[202:205], v[178:181], v[24:27]
	v_mfma_f32_16x16x32_bf16 v[16:19], v[210:213], v[178:181], v[16:19]
	v_mfma_f32_16x16x32_bf16 v[8:11], v[202:205], v[194:197], v[8:11]
	v_mfma_f32_16x16x32_bf16 v[0:3], v[210:213], v[194:197], v[0:3]
.Luph_s7:
	s_setprio 0
	s_add_i32 s96, s96, 2
	s_add_u32 s40, s40, 0x100
	s_addc_u32 s41, s41, 0
	s_add_u32 s26, s26, 0x100
	s_addc_u32 s27, s27, 0
	s_cmp_gt_u32 s96, 13
	s_barrier
	s_cbranch_scc0 .LBB0_66
	v_mul_f32_e32 v143, 0xbfb8aa3b, v124
	v_exp_f32_e32 v143, v143
	v_readlane_b32 s4, v254, 2
	v_lshl_or_b32 v144, s71, 7, v141
	v_readlane_b32 s5, v254, 3
	v_add_f32_e32 v143, 1.0, v143
	v_rcp_f32_e32 v143, v143
	v_lshl_add_u32 v142, s38, 8, v138
	s_cmp_eq_u32 s100, 2
	s_cbranch_scc0 .Luph_noshift
	v_add_u32_e32 v142, 0x80, v142
.Luph_noshift:
	v_ashrrev_i32_e32 v145, 31, v144
	s_and_b64 vcc, exec, s[22:23]
	v_mul_f32_e32 v124, v124, v143
	v_mul_f32_e32 v120, v124, v120
	v_mul_f32_e32 v124, 0xbfb8aa3b, v125
	v_exp_f32_e32 v124, v124
	s_mov_b32 s71, s28
	s_mov_b32 s38, s30
	s_mov_b64 s[42:43], s[36:37]
	v_add_f32_e32 v124, 1.0, v124
	v_rcp_f32_e32 v124, v124
	s_mov_b64 s[40:41], s[34:35]
	v_readlane_b32 s96, v255, 22
	v_mul_f32_e32 v124, v125, v124
	v_mul_f32_e32 v121, v124, v121
	v_mul_f32_e32 v124, 0xbfb8aa3b, v126
	v_exp_f32_e32 v124, v124
	s_nop 0
	v_add_f32_e32 v124, 1.0, v124
	v_rcp_f32_e32 v124, v124
	s_nop 0
	v_mul_f32_e32 v124, v126, v124
	v_mul_f32_e32 v122, v124, v122
	v_mul_f32_e32 v124, 0xbfb8aa3b, v127
	v_exp_f32_e32 v124, v124
	s_nop 0
	v_add_f32_e32 v124, 1.0, v124
	v_rcp_f32_e32 v124, v124
	s_nop 0
	v_mul_f32_e32 v124, v127, v124
	v_mul_f32_e32 v123, v124, v123
	v_mul_f32_e32 v124, 0xbfb8aa3b, v116
	v_exp_f32_e32 v124, v124
	s_nop 0
	v_add_f32_e32 v124, 1.0, v124
	v_rcp_f32_e32 v124, v124
	s_nop 0
	v_mul_f32_e32 v116, v116, v124
	v_mul_f32_e32 v112, v116, v112
	v_mul_f32_e32 v116, 0xbfb8aa3b, v117
	v_exp_f32_e32 v116, v116
	s_nop 0
	v_add_f32_e32 v116, 1.0, v116
	v_rcp_f32_e32 v116, v116
	s_nop 0
	v_mul_f32_e32 v116, v117, v116
	v_mul_f32_e32 v113, v116, v113
	v_mul_f32_e32 v116, 0xbfb8aa3b, v118
	v_exp_f32_e32 v116, v116
	v_cvt_pk_bf16_f32 v117, v122, v123
	s_nop 0
	v_add_f32_e32 v116, 1.0, v116
	v_rcp_f32_e32 v116, v116
	s_nop 0
	v_mul_f32_e32 v116, v118, v116
	v_mul_f32_e32 v114, v116, v114
	v_mul_f32_e32 v116, 0xbfb8aa3b, v119
	v_exp_f32_e32 v116, v116
	v_cvt_pk_bf16_f32 v118, v112, v113
	v_mov_b64_e32 v[112:113], s[4:5]
	s_movk_i32 s4, 0x1600
	v_add_f32_e32 v116, 1.0, v116
	v_rcp_f32_e32 v116, v116
	s_nop 0
	v_mul_f32_e32 v116, v119, v116
	v_mul_f32_e32 v115, v116, v115
	v_cvt_pk_bf16_f32 v116, v120, v121
	v_cvt_pk_bf16_f32 v119, v114, v115
	v_mad_i64_i32 v[120:121], s[26:27], v142, s4, v[112:113]
	v_lshlrev_b64 v[114:115], 1, v[144:145]
	v_lshl_add_u64 v[120:121], v[120:121], 0, v[114:115]
	global_store_dwordx4 v[120:121], v[116:119], off
	s_nop 1
	v_mul_f32_e32 v116, 0xbfb8aa3b, v108
	v_exp_f32_e32 v116, v116
	s_nop 0
	v_add_f32_e32 v116, 1.0, v116
	v_rcp_f32_e32 v116, v116
	s_nop 0
	v_mul_f32_e32 v108, v108, v116
	v_mul_f32_e32 v104, v108, v104
	v_mul_f32_e32 v108, 0xbfb8aa3b, v109
	v_exp_f32_e32 v108, v108
	s_nop 0
	v_add_f32_e32 v108, 1.0, v108
	v_rcp_f32_e32 v108, v108
	s_nop 0
	v_mul_f32_e32 v108, v109, v108
	v_mul_f32_e32 v105, v108, v105
	v_mul_f32_e32 v108, 0xbfb8aa3b, v110
	v_exp_f32_e32 v108, v108
	s_nop 0
	v_add_f32_e32 v108, 1.0, v108
	v_rcp_f32_e32 v108, v108
	s_nop 0
	v_mul_f32_e32 v108, v110, v108
	v_mul_f32_e32 v106, v108, v106
	v_mul_f32_e32 v108, 0xbfb8aa3b, v111
	v_exp_f32_e32 v108, v108
	s_nop 0
	v_add_f32_e32 v108, 1.0, v108
	v_rcp_f32_e32 v108, v108
	s_nop 0
	v_mul_f32_e32 v108, v111, v108
	v_mul_f32_e32 v107, v108, v107
	v_mul_f32_e32 v108, 0xbfb8aa3b, v100
	v_exp_f32_e32 v108, v108
	s_nop 0
	v_add_f32_e32 v108, 1.0, v108
	v_rcp_f32_e32 v108, v108
	s_nop 0
	v_mul_f32_e32 v100, v100, v108
	v_mul_f32_e32 v100, v100, v96
	v_mul_f32_e32 v96, 0xbfb8aa3b, v101
	v_exp_f32_e32 v96, v96
	s_nop 0
	v_add_f32_e32 v96, 1.0, v96
	v_rcp_f32_e32 v96, v96
	s_nop 0
	v_mul_f32_e32 v96, v101, v96
	v_mul_f32_e32 v101, v96, v97
	v_mul_f32_e32 v96, 0xbfb8aa3b, v102
	v_exp_f32_e32 v96, v96
	v_cvt_pk_bf16_f32 v97, v106, v107
	s_nop 0
	v_add_f32_e32 v96, 1.0, v96
	v_rcp_f32_e32 v96, v96
	s_nop 0
	v_mul_f32_e32 v96, v102, v96
	v_mul_f32_e32 v102, v96, v98
	v_mul_f32_e32 v96, 0xbfb8aa3b, v103
	v_exp_f32_e32 v96, v96
	v_cvt_pk_bf16_f32 v98, v100, v101
	s_nop 0
	v_add_f32_e32 v96, 1.0, v96
	v_rcp_f32_e32 v96, v96
	s_nop 0
	v_mul_f32_e32 v96, v103, v96
	v_or_b32_e32 v103, 16, v142
	v_mad_i64_i32 v[100:101], s[26:27], v103, s4, v[112:113]
	v_mul_f32_e32 v99, v96, v99
	v_cvt_pk_bf16_f32 v96, v104, v105
	v_lshl_add_u64 v[100:101], v[100:101], 0, v[114:115]
	v_cvt_pk_bf16_f32 v99, v102, v99
	global_store_dwordx4 v[100:101], v[96:99], off
	s_nop 1
	v_mul_f32_e32 v96, 0xbfb8aa3b, v92
	v_exp_f32_e32 v96, v96
	s_nop 0
	v_add_f32_e32 v96, 1.0, v96
	v_rcp_f32_e32 v96, v96
	s_nop 0
	v_mul_f32_e32 v92, v92, v96
	v_mul_f32_e32 v88, v92, v88
	v_mul_f32_e32 v92, 0xbfb8aa3b, v93
	v_exp_f32_e32 v92, v92
	s_nop 0
	v_add_f32_e32 v92, 1.0, v92
	v_rcp_f32_e32 v92, v92
	s_nop 0
	v_mul_f32_e32 v92, v93, v92
	v_mul_f32_e32 v89, v92, v89
	v_mul_f32_e32 v92, 0xbfb8aa3b, v94
	v_exp_f32_e32 v92, v92
	s_nop 0
	v_add_f32_e32 v92, 1.0, v92
	v_rcp_f32_e32 v92, v92
	s_nop 0
	v_mul_f32_e32 v92, v94, v92
	v_mul_f32_e32 v90, v92, v90
	v_mul_f32_e32 v92, 0xbfb8aa3b, v95
	v_exp_f32_e32 v92, v92
	s_nop 0
	v_add_f32_e32 v92, 1.0, v92
	v_rcp_f32_e32 v92, v92
	s_nop 0
	v_mul_f32_e32 v92, v95, v92
	v_mul_f32_e32 v91, v92, v91
	v_mul_f32_e32 v92, 0xbfb8aa3b, v84
	v_exp_f32_e32 v92, v92
	s_nop 0
	v_add_f32_e32 v92, 1.0, v92
	v_rcp_f32_e32 v92, v92
	s_nop 0
	v_mul_f32_e32 v84, v84, v92
	v_mul_f32_e32 v84, v84, v80
	v_mul_f32_e32 v80, 0xbfb8aa3b, v85
	v_exp_f32_e32 v80, v80
	s_nop 0
	v_add_f32_e32 v80, 1.0, v80
	v_rcp_f32_e32 v80, v80
	s_nop 0
	v_mul_f32_e32 v80, v85, v80
	v_mul_f32_e32 v85, v80, v81
	v_mul_f32_e32 v80, 0xbfb8aa3b, v86
	v_exp_f32_e32 v80, v80
	v_cvt_pk_bf16_f32 v81, v90, v91
	s_nop 0
	v_add_f32_e32 v80, 1.0, v80
	v_rcp_f32_e32 v80, v80
	s_nop 0
	v_mul_f32_e32 v80, v86, v80
	v_mul_f32_e32 v86, v80, v82
	v_mul_f32_e32 v80, 0xbfb8aa3b, v87
	v_exp_f32_e32 v80, v80
	v_cvt_pk_bf16_f32 v82, v84, v85
	s_nop 0
	v_add_f32_e32 v80, 1.0, v80
	v_rcp_f32_e32 v80, v80
	s_nop 0
	v_mul_f32_e32 v80, v87, v80
	v_or_b32_e32 v87, 32, v142
	v_mad_i64_i32 v[84:85], s[26:27], v87, s4, v[112:113]
	v_mul_f32_e32 v83, v80, v83
	v_cvt_pk_bf16_f32 v80, v88, v89
	v_lshl_add_u64 v[84:85], v[84:85], 0, v[114:115]
	v_cvt_pk_bf16_f32 v83, v86, v83
	global_store_dwordx4 v[84:85], v[80:83], off
	s_nop 1
	v_mul_f32_e32 v80, 0xbfb8aa3b, v76
	v_exp_f32_e32 v80, v80
	s_nop 0
	v_add_f32_e32 v80, 1.0, v80
	v_rcp_f32_e32 v80, v80
	s_nop 0
	v_mul_f32_e32 v76, v76, v80
	v_mul_f32_e32 v72, v76, v72
	v_mul_f32_e32 v76, 0xbfb8aa3b, v77
	v_exp_f32_e32 v76, v76
	s_nop 0
	v_add_f32_e32 v76, 1.0, v76
	v_rcp_f32_e32 v76, v76
	s_nop 0
	v_mul_f32_e32 v76, v77, v76
	v_mul_f32_e32 v73, v76, v73
	v_mul_f32_e32 v76, 0xbfb8aa3b, v78
	v_exp_f32_e32 v76, v76
	s_nop 0
	v_add_f32_e32 v76, 1.0, v76
	v_rcp_f32_e32 v76, v76
	s_nop 0
	v_mul_f32_e32 v76, v78, v76
	v_mul_f32_e32 v74, v76, v74
	v_mul_f32_e32 v76, 0xbfb8aa3b, v79
	v_exp_f32_e32 v76, v76
	s_nop 0
	v_add_f32_e32 v76, 1.0, v76
	v_rcp_f32_e32 v76, v76
	s_nop 0
	v_mul_f32_e32 v76, v79, v76
	v_mul_f32_e32 v75, v76, v75
	v_mul_f32_e32 v76, 0xbfb8aa3b, v68
	v_exp_f32_e32 v76, v76
	s_nop 0
	v_add_f32_e32 v76, 1.0, v76
	v_rcp_f32_e32 v76, v76
	s_nop 0
	v_mul_f32_e32 v68, v68, v76
	v_mul_f32_e32 v68, v68, v64
	v_mul_f32_e32 v64, 0xbfb8aa3b, v69
	v_exp_f32_e32 v64, v64
	s_nop 0
	v_add_f32_e32 v64, 1.0, v64
	v_rcp_f32_e32 v64, v64
	s_nop 0
	v_mul_f32_e32 v64, v69, v64
	v_mul_f32_e32 v69, v64, v65
	v_mul_f32_e32 v64, 0xbfb8aa3b, v70
	v_exp_f32_e32 v64, v64
	v_cvt_pk_bf16_f32 v65, v74, v75
	s_nop 0
	v_add_f32_e32 v64, 1.0, v64
	v_rcp_f32_e32 v64, v64
	s_nop 0
	v_mul_f32_e32 v64, v70, v64
	v_mul_f32_e32 v70, v64, v66
	v_mul_f32_e32 v64, 0xbfb8aa3b, v71
	v_exp_f32_e32 v64, v64
	v_cvt_pk_bf16_f32 v66, v68, v69
	s_nop 0
	v_add_f32_e32 v64, 1.0, v64
	v_rcp_f32_e32 v64, v64
	s_nop 0
	v_mul_f32_e32 v64, v71, v64
	v_or_b32_e32 v71, 48, v142
	v_mad_i64_i32 v[68:69], s[26:27], v71, s4, v[112:113]
	v_mul_f32_e32 v67, v64, v67
	v_lshl_add_u64 v[68:69], v[68:69], 0, v[114:115]
	v_cvt_pk_bf16_f32 v64, v72, v73
	v_cvt_pk_bf16_f32 v67, v70, v67
	global_store_dwordx4 v[68:69], v[64:67], off
	s_cmp_lg_u32 s100, 0
	s_cbranch_scc1 .Luph_nost
	s_nop 1
	v_mul_f32_e32 v65, 0xbfb8aa3b, v60
	v_exp_f32_e32 v65, v65
	v_add_u32_e32 v64, 0x80, v142
	v_add_f32_e32 v65, 1.0, v65
	v_rcp_f32_e32 v65, v65
	s_nop 0
	v_mul_f32_e32 v60, v60, v65
	v_mul_f32_e32 v56, v60, v56
	v_mul_f32_e32 v60, 0xbfb8aa3b, v61
	v_exp_f32_e32 v60, v60
	s_nop 0
	v_add_f32_e32 v60, 1.0, v60
	v_rcp_f32_e32 v60, v60
	s_nop 0
	v_mul_f32_e32 v60, v61, v60
	v_mul_f32_e32 v57, v60, v57
	v_mul_f32_e32 v60, 0xbfb8aa3b, v62
	v_exp_f32_e32 v60, v60
	s_nop 0
	v_add_f32_e32 v60, 1.0, v60
	v_rcp_f32_e32 v60, v60
	s_nop 0
	v_mul_f32_e32 v60, v62, v60
	v_mul_f32_e32 v58, v60, v58
	v_mul_f32_e32 v60, 0xbfb8aa3b, v63
	v_exp_f32_e32 v60, v60
	s_nop 0
	v_add_f32_e32 v60, 1.0, v60
	v_rcp_f32_e32 v60, v60
	s_nop 0
	v_mul_f32_e32 v60, v63, v60
	v_mul_f32_e32 v59, v60, v59
	v_mul_f32_e32 v60, 0xbfb8aa3b, v52
	v_exp_f32_e32 v60, v60
	s_nop 0
	v_add_f32_e32 v60, 1.0, v60
	v_rcp_f32_e32 v60, v60
	s_nop 0
	v_mul_f32_e32 v52, v52, v60
	v_mul_f32_e32 v52, v52, v48
	v_mul_f32_e32 v48, 0xbfb8aa3b, v53
	v_exp_f32_e32 v48, v48
	s_nop 0
	v_add_f32_e32 v48, 1.0, v48
	v_rcp_f32_e32 v48, v48
	s_nop 0
	v_mul_f32_e32 v48, v53, v48
	v_mul_f32_e32 v53, v48, v49
	v_mul_f32_e32 v48, 0xbfb8aa3b, v54
	v_exp_f32_e32 v48, v48
	v_cvt_pk_bf16_f32 v49, v58, v59
	s_nop 0
	v_add_f32_e32 v48, 1.0, v48
	v_rcp_f32_e32 v48, v48
	s_nop 0
	v_mul_f32_e32 v48, v54, v48
	v_mul_f32_e32 v54, v48, v50
	v_mul_f32_e32 v48, 0xbfb8aa3b, v55
	v_exp_f32_e32 v48, v48
	v_cvt_pk_bf16_f32 v50, v52, v53
	v_mad_i64_i32 v[52:53], s[26:27], v64, s4, v[112:113]
	v_add_f32_e32 v48, 1.0, v48
	v_rcp_f32_e32 v48, v48
	v_lshl_add_u64 v[52:53], v[52:53], 0, v[114:115]
	v_mul_f32_e32 v48, v55, v48
	v_mul_f32_e32 v51, v48, v51
	v_cvt_pk_bf16_f32 v48, v56, v57
	v_cvt_pk_bf16_f32 v51, v54, v51
	global_store_dwordx4 v[52:53], v[48:51], off
	s_nop 1
	v_mul_f32_e32 v48, 0xbfb8aa3b, v44
	v_exp_f32_e32 v48, v48
	s_nop 0
	v_add_f32_e32 v48, 1.0, v48
	v_rcp_f32_e32 v48, v48
	s_nop 0
	v_mul_f32_e32 v44, v44, v48
	v_mul_f32_e32 v40, v44, v40
	v_mul_f32_e32 v44, 0xbfb8aa3b, v45
	v_exp_f32_e32 v44, v44
	s_nop 0
	v_add_f32_e32 v44, 1.0, v44
	v_rcp_f32_e32 v44, v44
	s_nop 0
	v_mul_f32_e32 v44, v45, v44
	v_mul_f32_e32 v41, v44, v41
	v_mul_f32_e32 v44, 0xbfb8aa3b, v46
	v_exp_f32_e32 v44, v44
	s_nop 0
	v_add_f32_e32 v44, 1.0, v44
	v_rcp_f32_e32 v44, v44
	s_nop 0
	v_mul_f32_e32 v44, v46, v44
	v_mul_f32_e32 v42, v44, v42
	v_mul_f32_e32 v44, 0xbfb8aa3b, v47
	v_exp_f32_e32 v44, v44
	s_nop 0
	v_add_f32_e32 v44, 1.0, v44
	v_rcp_f32_e32 v44, v44
	s_nop 0
	v_mul_f32_e32 v44, v47, v44
	v_mul_f32_e32 v43, v44, v43
	v_mul_f32_e32 v44, 0xbfb8aa3b, v36
	v_exp_f32_e32 v44, v44
	s_nop 0
	v_add_f32_e32 v44, 1.0, v44
	v_rcp_f32_e32 v44, v44
	s_nop 0
	v_mul_f32_e32 v36, v36, v44
	v_mul_f32_e32 v36, v36, v32
	v_mul_f32_e32 v32, 0xbfb8aa3b, v37
	v_exp_f32_e32 v32, v32
	s_nop 0
	v_add_f32_e32 v32, 1.0, v32
	v_rcp_f32_e32 v32, v32
	s_nop 0
	v_mul_f32_e32 v32, v37, v32
	v_mul_f32_e32 v37, v32, v33
	v_mul_f32_e32 v32, 0xbfb8aa3b, v38
	v_exp_f32_e32 v32, v32
	v_cvt_pk_bf16_f32 v33, v42, v43
	s_nop 0
	v_add_f32_e32 v32, 1.0, v32
	v_rcp_f32_e32 v32, v32
	s_nop 0
	v_mul_f32_e32 v32, v38, v32
	v_mul_f32_e32 v38, v32, v34
	v_mul_f32_e32 v32, 0xbfb8aa3b, v39
	v_exp_f32_e32 v32, v32
	v_cvt_pk_bf16_f32 v34, v36, v37
	s_nop 0
	v_add_f32_e32 v32, 1.0, v32
	v_rcp_f32_e32 v32, v32
	s_nop 0
	v_mul_f32_e32 v32, v39, v32
	v_add_u32_e32 v39, 0x90, v142
	v_mad_i64_i32 v[36:37], s[26:27], v39, s4, v[112:113]
	v_mul_f32_e32 v35, v32, v35
	v_cvt_pk_bf16_f32 v32, v40, v41
	v_lshl_add_u64 v[36:37], v[36:37], 0, v[114:115]
	v_cvt_pk_bf16_f32 v35, v38, v35
	global_store_dwordx4 v[36:37], v[32:35], off
	s_nop 1
	v_mul_f32_e32 v32, 0xbfb8aa3b, v28
	v_exp_f32_e32 v32, v32
	s_nop 0
	v_add_f32_e32 v32, 1.0, v32
	v_rcp_f32_e32 v32, v32
	s_nop 0
	v_mul_f32_e32 v28, v28, v32
	v_mul_f32_e32 v24, v28, v24
	v_mul_f32_e32 v28, 0xbfb8aa3b, v29
	v_exp_f32_e32 v28, v28
	s_nop 0
	v_add_f32_e32 v28, 1.0, v28
	v_rcp_f32_e32 v28, v28
	s_nop 0
	v_mul_f32_e32 v28, v29, v28
	v_mul_f32_e32 v25, v28, v25
	v_mul_f32_e32 v28, 0xbfb8aa3b, v30
	v_exp_f32_e32 v28, v28
	s_nop 0
	v_add_f32_e32 v28, 1.0, v28
	v_rcp_f32_e32 v28, v28
	s_nop 0
	v_mul_f32_e32 v28, v30, v28
	v_mul_f32_e32 v26, v28, v26
	v_mul_f32_e32 v28, 0xbfb8aa3b, v31
	v_exp_f32_e32 v28, v28
	s_nop 0
	v_add_f32_e32 v28, 1.0, v28
	v_rcp_f32_e32 v28, v28
	s_nop 0
	v_mul_f32_e32 v28, v31, v28
	v_mul_f32_e32 v27, v28, v27
	v_mul_f32_e32 v28, 0xbfb8aa3b, v20
	v_exp_f32_e32 v28, v28
	s_nop 0
	v_add_f32_e32 v28, 1.0, v28
	v_rcp_f32_e32 v28, v28
	s_nop 0
	v_mul_f32_e32 v20, v20, v28
	v_mul_f32_e32 v20, v20, v16
	v_mul_f32_e32 v16, 0xbfb8aa3b, v21
	v_exp_f32_e32 v16, v16
	s_nop 0
	v_add_f32_e32 v16, 1.0, v16
	v_rcp_f32_e32 v16, v16
	s_nop 0
	v_mul_f32_e32 v16, v21, v16
	v_mul_f32_e32 v21, v16, v17
	v_mul_f32_e32 v16, 0xbfb8aa3b, v22
	v_exp_f32_e32 v16, v16
	v_cvt_pk_bf16_f32 v17, v26, v27
	s_nop 0
	v_add_f32_e32 v16, 1.0, v16
	v_rcp_f32_e32 v16, v16
	s_nop 0
	v_mul_f32_e32 v16, v22, v16
	v_mul_f32_e32 v22, v16, v18
	v_mul_f32_e32 v16, 0xbfb8aa3b, v23
	v_exp_f32_e32 v16, v16
	v_cvt_pk_bf16_f32 v18, v20, v21
	s_nop 0
	v_add_f32_e32 v16, 1.0, v16
	v_rcp_f32_e32 v16, v16
	s_nop 0
	v_mul_f32_e32 v16, v23, v16
	v_add_u32_e32 v23, 0xa0, v142
	v_mad_i64_i32 v[20:21], s[26:27], v23, s4, v[112:113]
	v_mul_f32_e32 v19, v16, v19
	v_cvt_pk_bf16_f32 v16, v24, v25
	v_lshl_add_u64 v[20:21], v[20:21], 0, v[114:115]
	v_cvt_pk_bf16_f32 v19, v22, v19
	global_store_dwordx4 v[20:21], v[16:19], off
	s_nop 1
	v_mul_f32_e32 v16, 0xbfb8aa3b, v12
	v_exp_f32_e32 v16, v16
	s_nop 0
	v_add_f32_e32 v16, 1.0, v16
	v_rcp_f32_e32 v16, v16
	s_nop 0
	v_mul_f32_e32 v12, v12, v16
	v_mul_f32_e32 v8, v12, v8
	v_mul_f32_e32 v12, 0xbfb8aa3b, v13
	v_exp_f32_e32 v12, v12
	s_nop 0
	v_add_f32_e32 v12, 1.0, v12
	v_rcp_f32_e32 v12, v12
	s_nop 0
	v_mul_f32_e32 v12, v13, v12
	v_mul_f32_e32 v9, v12, v9
	v_mul_f32_e32 v12, 0xbfb8aa3b, v14
	v_exp_f32_e32 v12, v12
	s_nop 0
	v_add_f32_e32 v12, 1.0, v12
	v_rcp_f32_e32 v12, v12
	s_nop 0
	v_mul_f32_e32 v12, v14, v12
	v_mul_f32_e32 v10, v12, v10
	v_mul_f32_e32 v12, 0xbfb8aa3b, v15
	v_exp_f32_e32 v12, v12
	s_nop 0
	v_add_f32_e32 v12, 1.0, v12
	v_rcp_f32_e32 v12, v12
	s_nop 0
	v_mul_f32_e32 v12, v15, v12
	v_mul_f32_e32 v11, v12, v11
	v_mul_f32_e32 v12, 0xbfb8aa3b, v4
	v_exp_f32_e32 v12, v12
	s_nop 0
	v_add_f32_e32 v12, 1.0, v12
	v_rcp_f32_e32 v12, v12
	s_nop 0
	v_mul_f32_e32 v4, v4, v12
	v_mul_f32_e32 v4, v4, v0
	v_mul_f32_e32 v0, 0xbfb8aa3b, v5
	v_exp_f32_e32 v0, v0
	s_nop 0
	v_add_f32_e32 v0, 1.0, v0
	v_rcp_f32_e32 v0, v0
	s_nop 0
	v_mul_f32_e32 v0, v5, v0
	v_mul_f32_e32 v5, v0, v1
	v_mul_f32_e32 v0, 0xbfb8aa3b, v6
	v_exp_f32_e32 v0, v0
	v_cvt_pk_bf16_f32 v1, v10, v11
	s_nop 0
	v_add_f32_e32 v0, 1.0, v0
	v_rcp_f32_e32 v0, v0
	s_nop 0
	v_mul_f32_e32 v0, v6, v0
	v_mul_f32_e32 v6, v0, v2
	v_mul_f32_e32 v0, 0xbfb8aa3b, v7
	v_exp_f32_e32 v0, v0
	v_cvt_pk_bf16_f32 v2, v4, v5
	s_nop 0
	v_add_f32_e32 v0, 1.0, v0
	v_rcp_f32_e32 v0, v0
	s_nop 0
	v_mul_f32_e32 v0, v7, v0
	v_add_u32_e32 v7, 0xb0, v142
	v_mad_i64_i32 v[4:5], s[26:27], v7, s4, v[112:113]
	v_mul_f32_e32 v3, v0, v3
	v_lshl_add_u64 v[4:5], v[4:5], 0, v[114:115]
	v_cvt_pk_bf16_f32 v0, v8, v9
	v_cvt_pk_bf16_f32 v3, v6, v3
	global_store_dwordx4 v[4:5], v[0:3], off
.Luph_nost:
	s_mov_b32 s100, s101
	s_cbranch_vccz .LBB0_63
	s_waitcnt vmcnt(0)
	v_readlane_b32 s64, v255, 43
	v_readlane_b32 s65, v255, 44
	s_cmpk_gt_u32 s46, 0xff
	s_mov_b64 s[84:85], s[64:65]
	s_movk_i32 s33, 0x3fff
	s_mov_b32 s70, 0xbfb8aa3b
	s_mov_b32 s71, 0x42ce8ed0
	v_readlane_b32 s66, v255, 45
	v_readlane_b32 s67, v255, 46
	s_cbranch_scc1 .LBB0_70
	s_barrier
